# ps1 + half-2 QK MFMA pairs issued back-to-back (VALU moved behind the pair, row-sum chain temp renamed) in the prompt-diff main loop
# baseline (speedup 1.0000x reference)
.LBB0_463:
	s_mov_b32 s8, s60
	s_mov_b32 s9, s16
	s_mov_b32 s10, s59
	ds_read_b128 v[4:7], v219 offset:1024
	v_lshl_add_u32 v207, s11, 14, v214
	v_add_f32_e32 v2, v100, v101
	v_add_f32_e32 v2, v102, v2
	v_add_f32_e32 v2, v103, v2
	v_add_f32_e32 v2, v104, v2
	v_add_f32_e32 v2, v105, v2
	v_cvt_pk_bf16_f32 v160, v100, v101
	v_cvt_pk_bf16_f32 v161, v102, v103
	s_waitcnt lgkmcnt(1)
	v_mfma_f32_32x32x16_bf16 v[132:147], v[192:195], v[116:119], 0
	v_mfma_f32_32x32x16_bf16 v[116:131], v[184:187], v[116:119], 0
	v_add_f32_e32 v2, v106, v2
	v_add_f32_e32 v2, v107, v2
	v_add_f32_e32 v2, v108, v2
	v_add_f32_e32 v2, v109, v2
	v_cvt_pk_bf16_f32 v162, v104, v105
	v_cvt_pk_bf16_f32 v163, v106, v107
	ds_read_b128 v[10:13], v219 offset:2048
	ds_read_b64_tr_b16 v[14:15], v207 offset:24576
	ds_read_b64_tr_b16 v[16:17], v207 offset:25088
	v_add_f32_e32 v2, v110, v2
	v_add_f32_e32 v2, v111, v2
	v_add_f32_e32 v2, v112, v2
	v_add_f32_e32 v2, v113, v2
	v_cvt_pk_bf16_f32 v156, v108, v109
	v_cvt_pk_bf16_f32 v157, v110, v111
	s_waitcnt lgkmcnt(3)
	v_mfma_f32_32x32x16_bf16 v[132:147], v[188:191], v[4:7], v[132:147]
	v_mfma_f32_32x32x16_bf16 v[116:131], v[180:183], v[4:7], v[116:131]
	v_add_f32_e32 v2, v114, v2
	v_add_f32_e32 v2, v115, v2
	v_add_f32_e32 v2, v84, v2
	v_add_f32_e32 v2, v85, v2
	v_cvt_pk_bf16_f32 v158, v112, v113
	v_cvt_pk_bf16_f32 v159, v114, v115
	ds_read_b128 v[4:7], v219 offset:3072
	ds_read_b64_tr_b16 v[100:101], v207 offset:28672
	ds_read_b64_tr_b16 v[102:103], v207 offset:29184
	v_add_f32_e32 v2, v86, v2
	v_add_f32_e32 v2, v87, v2
	v_add_f32_e32 v2, v88, v2
	v_add_f32_e32 v2, v89, v2
	v_cvt_pk_bf16_f32 v152, v84, v85
	v_cvt_pk_bf16_f32 v153, v86, v87
	s_waitcnt lgkmcnt(5)
	v_mfma_f32_32x32x16_bf16 v[132:147], v[176:179], v[10:13], v[132:147]
	v_mfma_f32_32x32x16_bf16 v[116:131], v[172:175], v[10:13], v[116:131]
	v_add_f32_e32 v2, v90, v2
	v_add_f32_e32 v2, v91, v2
	v_add_f32_e32 v2, v92, v2
	v_add_f32_e32 v2, v93, v2
	v_cvt_pk_bf16_f32 v154, v88, v89
	v_cvt_pk_bf16_f32 v155, v90, v91
	ds_read_b64_tr_b16 v[84:85], v207 offset:25600
	ds_read_b64_tr_b16 v[86:87], v207 offset:26112
	v_add_f32_e32 v2, v94, v2
	v_add_f32_e32 v2, v95, v2
	v_add_f32_e32 v2, v96, v2
	v_add_f32_e32 v2, v97, v2
	v_cvt_pk_bf16_f32 v148, v92, v93
	v_cvt_pk_bf16_f32 v149, v94, v95
	s_waitcnt lgkmcnt(4)
	v_mfma_f32_32x32x16_bf16 v[132:147], v[168:171], v[4:7], v[132:147]
	v_mfma_f32_32x32x16_bf16 v[116:131], v[164:167], v[4:7], v[116:131]
	v_add_f32_e32 v2, v98, v2
	v_add_f32_e32 v2, v99, v2
	v_cvt_pk_bf16_f32 v150, v96, v97
	v_cvt_pk_bf16_f32 v151, v98, v99
	v_add_f32_e32 v2, v225, v2
	ds_read_b64_tr_b16 v[4:5], v207 offset:29696
	ds_read_b64_tr_b16 v[6:7], v207 offset:30208
	v_mfma_f32_32x32x16_bf16 v[68:83], v[160:163], v[14:17], v[68:83]
	v_exp_f32_e32 v132, v132
	v_exp_f32_e32 v133, v133
	ds_read_b64_tr_b16 v[14:15], v207 offset:26624
	ds_read_b64_tr_b16 v[16:17], v207 offset:27136
	s_waitcnt lgkmcnt(6)
	v_mfma_f32_32x32x16_bf16 v[52:67], v[160:163], v[100:103], v[52:67]
	v_exp_f32_e32 v134, v134
	v_exp_f32_e32 v135, v135
	s_add_u32 s98, s6, s28
	s_addc_u32 s99, s7, s29
	v_lshl_add_u64 v[254:255], v[204:205], 0, s[98:99]
	s_lshl_b32 s100, s59, 13
	s_add_i32 s100, s100, s49
	s_mov_b32 m0, s100
	s_nop 0
	global_load_lds_dwordx4 v[254:255], off
	ds_read_b64_tr_b16 v[88:89], v207 offset:30720
	ds_read_b64_tr_b16 v[90:91], v207 offset:31232
	s_waitcnt lgkmcnt(6)
	v_mfma_f32_32x32x16_bf16 v[68:83], v[156:159], v[84:87], v[68:83]
	v_exp_f32_e32 v136, v136
	v_exp_f32_e32 v137, v137
	ds_read_b64_tr_b16 v[84:85], v207 offset:27648
	ds_read_b64_tr_b16 v[86:87], v207 offset:28160
	s_waitcnt lgkmcnt(6)
	v_mfma_f32_32x32x16_bf16 v[52:67], v[156:159], v[4:7], v[52:67]
	v_exp_f32_e32 v138, v138
	v_exp_f32_e32 v139, v139
	ds_read_b64_tr_b16 v[4:5], v207 offset:31744
	ds_read_b64_tr_b16 v[6:7], v207 offset:32256
	s_waitcnt lgkmcnt(6)
	v_mfma_f32_32x32x16_bf16 v[68:83], v[152:155], v[14:17], v[68:83]
	v_exp_f32_e32 v140, v140
	v_exp_f32_e32 v141, v141
	s_add_u32 s98, s6, s30
	s_addc_u32 s99, s7, s31
	v_lshl_add_u64 v[254:255], v[8:9], 0, s[98:99]
	s_lshl_b32 s100, s60, 14
	s_add_i32 s100, s100, s58
	s_mov_b32 m0, s100
	s_nop 0
	global_load_lds_dwordx4 v[254:255], off
	ds_read_b64_tr_b16 v[14:15], v207 offset:32768
	ds_read_b64_tr_b16 v[16:17], v207 offset:33280
	s_waitcnt lgkmcnt(6)
	v_mfma_f32_32x32x16_bf16 v[52:67], v[152:155], v[88:91], v[52:67]
	v_exp_f32_e32 v142, v142
	v_exp_f32_e32 v143, v143
	ds_read_b64_tr_b16 v[88:89], v207 offset:36864
	ds_read_b64_tr_b16 v[90:91], v207 offset:37376
	s_waitcnt lgkmcnt(6)
	v_mfma_f32_32x32x16_bf16 v[68:83], v[148:151], v[84:87], v[68:83]
	v_exp_f32_e32 v144, v144
	v_exp_f32_e32 v145, v145
	ds_read_b64_tr_b16 v[84:85], v207 offset:33792
	ds_read_b64_tr_b16 v[86:87], v207 offset:34304
	s_waitcnt lgkmcnt(6)
	v_mfma_f32_32x32x16_bf16 v[52:67], v[148:151], v[4:7], v[52:67]
	v_exp_f32_e32 v146, v146
	v_exp_f32_e32 v147, v147
	ds_read_b64_tr_b16 v[92:93], v207 offset:37888
	ds_read_b64_tr_b16 v[94:95], v207 offset:38400
	s_lshl_b32 s11, s60, 13
	v_add_u32_e32 v4, s11, v222
	ds_read_b128 v[96:99], v4
	ds_read_b128 v[164:167], v4 offset:512
	s_waitcnt lgkmcnt(8)
	v_mfma_f32_32x32x16_bf16 v[36:51], v[160:163], v[14:17], v[36:51]
	v_exp_f32_e32 v116, v116
	v_exp_f32_e32 v117, v117
	ds_read_b64_tr_b16 v[14:15], v207 offset:34816
	ds_read_b64_tr_b16 v[16:17], v207 offset:35328
	ds_read_b128 v[168:171], v4 offset:2048
	ds_read_b128 v[172:175], v4 offset:2560
	s_waitcnt lgkmcnt(10)
	v_mfma_f32_32x32x16_bf16 v[20:35], v[160:163], v[88:91], v[20:35]
	v_exp_f32_e32 v118, v118
	v_exp_f32_e32 v119, v119
	ds_read_b64_tr_b16 v[88:89], v207 offset:38912
	ds_read_b64_tr_b16 v[90:91], v207 offset:39424
	ds_read_b128 v[176:179], v4 offset:4096
	ds_read_b128 v[180:183], v4 offset:4608
	s_waitcnt lgkmcnt(12)
	v_mfma_f32_32x32x16_bf16 v[36:51], v[156:159], v[84:87], v[36:51]
	v_exp_f32_e32 v120, v120
	v_exp_f32_e32 v121, v121
	ds_read_b64_tr_b16 v[84:85], v207 offset:35840
	ds_read_b64_tr_b16 v[86:87], v207 offset:36352
	ds_read_b128 v[184:187], v4 offset:6144
	ds_read_b128 v[4:7], v4 offset:6656
	s_waitcnt lgkmcnt(14)
	v_mfma_f32_32x32x16_bf16 v[20:35], v[156:159], v[92:95], v[20:35]
	v_exp_f32_e32 v122, v122
	v_exp_f32_e32 v123, v123
	ds_read_b64_tr_b16 v[92:93], v207 offset:39936
	ds_read_b64_tr_b16 v[94:95], v207 offset:40448
	s_waitcnt lgkmcnt(12)
	v_mfma_f32_32x32x16_bf16 v[36:51], v[152:155], v[14:17], v[36:51]
	v_exp_f32_e32 v124, v124
	v_exp_f32_e32 v125, v125
	ds_read_b128 v[14:17], v219
	s_waitcnt lgkmcnt(9)
	v_mfma_f32_32x32x16_bf16 v[20:35], v[152:155], v[88:91], v[20:35]
	v_exp_f32_e32 v126, v126
	v_exp_f32_e32 v127, v127
	s_add_u32 s98, s6, s34
	s_addc_u32 s99, s7, s35
	v_lshl_add_u64 v[254:255], v[8:9], 0, s[98:99]
	s_lshl_b32 s100, s60, 14
	s_add_i32 s100, s100, s58
	s_addk_i32 s100, 0x2000
	s_mov_b32 m0, s100
	s_nop 0
	global_load_lds_dwordx4 v[254:255], off
	s_waitcnt lgkmcnt(5)
	v_mfma_f32_32x32x16_bf16 v[36:51], v[148:151], v[84:87], v[36:51]
	v_exp_f32_e32 v128, v128
	v_exp_f32_e32 v129, v129
	s_waitcnt lgkmcnt(1)
	v_mfma_f32_32x32x16_bf16 v[20:35], v[148:151], v[92:95], v[20:35]
	v_exp_f32_e32 v130, v130
	v_exp_f32_e32 v131, v131
	s_waitcnt vmcnt(3) lgkmcnt(0)
	s_barrier
	s_add_i32 s16, s60, 1
	s_cmp_lg_u32 s60, 2
	s_cselect_b32 s59, s16, 0
	ds_read_b128 v[188:191], v219 offset:1024
	v_lshl_add_u32 v207, s10, 14, v214
	s_waitcnt lgkmcnt(1)
	v_mfma_f32_32x32x16_bf16 v[100:115], v[96:99], v[14:17], 0
	v_mfma_f32_32x32x16_bf16 v[84:99], v[164:167], v[14:17], 0
	v_add_f32_e32 v228, v132, v133
	v_add_f32_e32 v228, v134, v228
	v_add_f32_e32 v228, v135, v228
	v_add_f32_e32 v228, v136, v228
	v_add_f32_e32 v228, v137, v228
	v_cvt_pk_bf16_f32 v160, v132, v133
	v_cvt_pk_bf16_f32 v161, v134, v135
	s_nop 0
	v_add_f32_e32 v228, v138, v228
	v_add_f32_e32 v228, v139, v228
	v_add_f32_e32 v228, v140, v228
	v_add_f32_e32 v228, v141, v228
	v_cvt_pk_bf16_f32 v162, v136, v137
	v_cvt_pk_bf16_f32 v163, v138, v139
	ds_read_b128 v[14:17], v219 offset:2048
	ds_read_b64_tr_b16 v[132:133], v207 offset:24576
	ds_read_b64_tr_b16 v[134:135], v207 offset:25088
	s_waitcnt lgkmcnt(3)
	v_mfma_f32_32x32x16_bf16 v[100:115], v[168:171], v[188:191], v[100:115]
	v_mfma_f32_32x32x16_bf16 v[84:99], v[172:175], v[188:191], v[84:99]
	v_add_f32_e32 v228, v142, v228
	v_add_f32_e32 v228, v143, v228
	v_add_f32_e32 v228, v144, v228
	v_add_f32_e32 v228, v145, v228
	v_cvt_pk_bf16_f32 v156, v140, v141
	v_cvt_pk_bf16_f32 v157, v142, v143
	v_add_f32_e32 v228, v146, v228
	v_add_f32_e32 v228, v147, v228
	v_add_f32_e32 v228, v116, v228
	v_add_f32_e32 v228, v117, v228
	v_cvt_pk_bf16_f32 v158, v144, v145
	v_cvt_pk_bf16_f32 v159, v146, v147
	ds_read_b128 v[136:139], v219 offset:3072
	ds_read_b64_tr_b16 v[140:141], v207 offset:28672
	ds_read_b64_tr_b16 v[142:143], v207 offset:29184
	s_waitcnt lgkmcnt(5)
	v_mfma_f32_32x32x16_bf16 v[100:115], v[176:179], v[14:17], v[100:115]
	v_mfma_f32_32x32x16_bf16 v[84:99], v[180:183], v[14:17], v[84:99]
	v_add_f32_e32 v228, v118, v228
	v_add_f32_e32 v228, v119, v228
	v_add_f32_e32 v228, v120, v228
	v_add_f32_e32 v228, v121, v228
	v_cvt_pk_bf16_f32 v152, v116, v117
	v_cvt_pk_bf16_f32 v153, v118, v119
	v_add_f32_e32 v228, v122, v228
	v_add_f32_e32 v228, v123, v228
	v_add_f32_e32 v228, v124, v228
	v_add_f32_e32 v228, v125, v228
	v_cvt_pk_bf16_f32 v154, v120, v121
	v_cvt_pk_bf16_f32 v155, v122, v123
	ds_read_b64_tr_b16 v[14:15], v207 offset:25600
	ds_read_b64_tr_b16 v[16:17], v207 offset:26112
	s_waitcnt lgkmcnt(4)
	v_mfma_f32_32x32x16_bf16 v[100:115], v[184:187], v[136:139], v[100:115]
	v_mfma_f32_32x32x16_bf16 v[84:99], v[4:7], v[136:139], v[84:99]
	v_add_f32_e32 v228, v126, v228
	v_add_f32_e32 v228, v127, v228
	v_add_f32_e32 v228, v128, v228
	v_add_f32_e32 v228, v129, v228
	v_cvt_pk_bf16_f32 v148, v124, v125
	v_cvt_pk_bf16_f32 v149, v126, v127
	v_add_f32_e32 v228, v130, v228
	v_add_f32_e32 v228, v131, v228
	v_cvt_pk_bf16_f32 v150, v128, v129
	v_cvt_pk_bf16_f32 v151, v130, v131
	v_add_f32_e32 v225, v2, v228
	ds_read_b64_tr_b16 v[4:5], v207 offset:29696
	ds_read_b64_tr_b16 v[6:7], v207 offset:30208
	v_mfma_f32_32x32x16_bf16 v[68:83], v[160:163], v[132:135], v[68:83]
	v_exp_f32_e32 v100, v100
	v_exp_f32_e32 v101, v101
	ds_read_b64_tr_b16 v[10:11], v207 offset:26624
	ds_read_b64_tr_b16 v[12:13], v207 offset:27136
	s_waitcnt lgkmcnt(6)
; #define TWAIT_BAR(N) asm volatile("s_waitcnt vmcnt(" #N ") lgkmcnt(0)\n\ts_barrier" ::: "memory")
; #define RESC() do { if constexpr (!NOMAX) if (resc) { asm volatile("s_waitcnt lgkmcnt(0)" ::: "memory"); \
;         _Pragma("unroll") for (int d_ = 0; d_ < 2; ++d_) _Pragma("unroll") for (int r = 0; r < 16; ++r) o[d_][r] *= wsf[crow(r, hi)]; } } while (0)
; #define ROT() do { sl_prev = sl_cur; sl_cur = sl_next; sl_next = (sl_next == 2 * SLOTB) ? 0 : sl_next + SLOTB; } while (0)
; #define RESC() do { if constexpr (!NOMAX) if (resc) { asm volatile("s_waitcnt lgkmcnt(0)" ::: "memory"); \
;         _Pragma("unroll") for (int d_ = 0; d_ < 4; ++d_) _Pragma("unroll") for (int r = 0; r < 16; ++r) o[d_][r] *= wsf[crow(r, hi)]; } } while (0)
; #define ROT() do { sl_prev = sl_cur; sl_cur = sl_next; sl_next = (sl_next == 2) ? 0 : sl_next + 1; } while (0)
; #define RESC() do { if (resc) { asm volatile("s_waitcnt lgkmcnt(0)" ::: "memory"); \
;         _Pragma("unroll") for (int d_ = 0; d_ < 4; ++d_) _Pragma("unroll") for (int r = 0; r < 16; ++r) o[d_][r] *= wsf[crow(r, hi)]; } } while (0)
; template <bool NOMAX>
; __device__ __forceinline__ void diff_unit(const AttnCtx& C, int u, LAS unsigned char* lds) {
;     ...
;     int kk = 1;
;     for (; kk + 7 < n; kk += 2) {
;         STEP(pB0, pB1, pA0, pA1, kk, true, true, true, false);     TWAIT_BAR(3); RESC(); ROT();
;         STEP(pA0, pA1, pB0, pB1, kk + 1, true, true, true, false); TWAIT_BAR(3); RESC(); ROT();
	v_mfma_f32_32x32x16_bf16 v[52:67], v[160:163], v[140:143], v[52:67]
	v_exp_f32_e32 v102, v102
	v_exp_f32_e32 v103, v103
	s_add_u32 s98, s6, s36
	s_addc_u32 s99, s7, s37
	v_lshl_add_u64 v[254:255], v[204:205], 0, s[98:99]
	s_lshl_b32 s100, s60, 13
	s_add_i32 s100, s100, s49
	s_mov_b32 m0, s100
	s_nop 0
	global_load_lds_dwordx4 v[254:255], off
	ds_read_b64_tr_b16 v[116:117], v207 offset:30720
	ds_read_b64_tr_b16 v[118:119], v207 offset:31232
	s_waitcnt lgkmcnt(6)
	v_mfma_f32_32x32x16_bf16 v[68:83], v[156:159], v[14:17], v[68:83]
	v_exp_f32_e32 v104, v104
	v_exp_f32_e32 v105, v105
	ds_read_b64_tr_b16 v[14:15], v207 offset:27648
	ds_read_b64_tr_b16 v[16:17], v207 offset:28160
	s_waitcnt lgkmcnt(6)
	v_mfma_f32_32x32x16_bf16 v[52:67], v[156:159], v[4:7], v[52:67]
	v_exp_f32_e32 v106, v106
	v_exp_f32_e32 v107, v107
	ds_read_b64_tr_b16 v[4:5], v207 offset:31744
	ds_read_b64_tr_b16 v[6:7], v207 offset:32256
	s_waitcnt lgkmcnt(6)
	v_mfma_f32_32x32x16_bf16 v[68:83], v[152:155], v[10:13], v[68:83]
	v_exp_f32_e32 v108, v108
	v_exp_f32_e32 v109, v109
	s_add_u32 s98, s6, s38
	s_addc_u32 s99, s7, s39
	v_lshl_add_u64 v[254:255], v[8:9], 0, s[98:99]
	s_lshl_b32 s100, s59, 14
	s_add_i32 s100, s100, s58
	s_mov_b32 m0, s100
	s_nop 0
	global_load_lds_dwordx4 v[254:255], off
	ds_read_b64_tr_b16 v[10:11], v207 offset:32768
	ds_read_b64_tr_b16 v[12:13], v207 offset:33280
	s_waitcnt lgkmcnt(6)
	v_mfma_f32_32x32x16_bf16 v[52:67], v[152:155], v[116:119], v[52:67]
	v_exp_f32_e32 v110, v110
	v_exp_f32_e32 v111, v111
	ds_read_b64_tr_b16 v[116:117], v207 offset:36864
	ds_read_b64_tr_b16 v[118:119], v207 offset:37376
	s_waitcnt lgkmcnt(6)
	v_mfma_f32_32x32x16_bf16 v[68:83], v[148:151], v[14:17], v[68:83]
	v_exp_f32_e32 v112, v112
	v_exp_f32_e32 v113, v113
	ds_read_b64_tr_b16 v[14:15], v207 offset:33792
	ds_read_b64_tr_b16 v[16:17], v207 offset:34304
	s_waitcnt lgkmcnt(6)
	v_mfma_f32_32x32x16_bf16 v[52:67], v[148:151], v[4:7], v[52:67]
	v_exp_f32_e32 v114, v114
	v_exp_f32_e32 v115, v115
	ds_read_b64_tr_b16 v[4:5], v207 offset:37888
	ds_read_b64_tr_b16 v[6:7], v207 offset:38400
	v_lshl_add_u32 v2, s59, 13, v222
	ds_read_b128 v[192:195], v2
	ds_read_b128 v[184:187], v2 offset:512
	s_waitcnt lgkmcnt(8)
	v_mfma_f32_32x32x16_bf16 v[36:51], v[160:163], v[10:13], v[36:51]
	v_exp_f32_e32 v84, v84
	v_exp_f32_e32 v85, v85
	ds_read_b64_tr_b16 v[10:11], v207 offset:34816
	ds_read_b64_tr_b16 v[12:13], v207 offset:35328
	ds_read_b128 v[188:191], v2 offset:2048
	ds_read_b128 v[180:183], v2 offset:2560
	s_waitcnt lgkmcnt(10)
	v_mfma_f32_32x32x16_bf16 v[20:35], v[160:163], v[116:119], v[20:35]
	v_exp_f32_e32 v86, v86
	v_exp_f32_e32 v87, v87
	ds_read_b64_tr_b16 v[120:121], v207 offset:38912
	ds_read_b64_tr_b16 v[122:123], v207 offset:39424
	ds_read_b128 v[176:179], v2 offset:4096
	ds_read_b128 v[172:175], v2 offset:4608
	s_waitcnt lgkmcnt(12)
	v_mfma_f32_32x32x16_bf16 v[36:51], v[156:159], v[14:17], v[36:51]
	v_exp_f32_e32 v88, v88
	v_exp_f32_e32 v89, v89
	ds_read_b64_tr_b16 v[14:15], v207 offset:35840
	ds_read_b64_tr_b16 v[16:17], v207 offset:36352
	ds_read_b128 v[168:171], v2 offset:6144
	ds_read_b128 v[164:167], v2 offset:6656
	s_waitcnt lgkmcnt(14)
	v_mfma_f32_32x32x16_bf16 v[20:35], v[156:159], v[4:7], v[20:35]
	v_exp_f32_e32 v90, v90
	v_exp_f32_e32 v91, v91
	ds_read_b64_tr_b16 v[4:5], v207 offset:39936
	ds_read_b64_tr_b16 v[6:7], v207 offset:40448
	s_waitcnt lgkmcnt(12)
	v_mfma_f32_32x32x16_bf16 v[36:51], v[152:155], v[10:13], v[36:51]
	v_exp_f32_e32 v92, v92
	v_exp_f32_e32 v93, v93
	ds_read_b128 v[116:119], v219
	s_waitcnt lgkmcnt(9)
	v_mfma_f32_32x32x16_bf16 v[20:35], v[152:155], v[120:123], v[20:35]
	v_exp_f32_e32 v94, v94
	v_exp_f32_e32 v95, v95
	s_add_u32 s98, s6, s40
	s_addc_u32 s99, s7, s41
	v_lshl_add_u64 v[254:255], v[8:9], 0, s[98:99]
	s_lshl_b32 s100, s59, 14
	s_add_i32 s100, s100, s58
	s_addk_i32 s100, 0x2000
	s_mov_b32 m0, s100
	s_nop 0
	global_load_lds_dwordx4 v[254:255], off
	s_waitcnt lgkmcnt(5)
	v_mfma_f32_32x32x16_bf16 v[36:51], v[148:151], v[14:17], v[36:51]
	v_exp_f32_e32 v96, v96
	v_exp_f32_e32 v97, v97
	s_waitcnt lgkmcnt(1)
	v_mfma_f32_32x32x16_bf16 v[20:35], v[148:151], v[4:7], v[20:35]
	v_exp_f32_e32 v98, v98
	v_exp_f32_e32 v99, v99
	s_add_i32 s10, s59, 1
	s_cmp_lg_u32 s59, 2
	s_waitcnt vmcnt(3) lgkmcnt(0)
	s_barrier
	s_cselect_b32 s60, s10, 0
	s_add_i32 s16, s9, 2
	s_add_u32 s6, s6, 0x20000
	v_cmp_ge_u32_e32 vcc, s16, v226
	s_addc_u32 s7, s7, 0
	s_mov_b32 s11, s8
	s_cbranch_vccz .LBB0_463
	v_mov_b32_e32 v228, 0x260
	s_add_i32 s16, s9, -5
	s_branch .LBB0_467
